# merged gate/up K loop: all 16 LDS fragment reads of a section issued before its two LDS-DMA loads (DMA addresses precomputed into spare registers)
# baseline (speedup 1.0000x reference)
; #define PG8_STAGE(bufoff, gbase, voff) do { _Pragma("unroll") for (int _i = 0; _i < 2; ++_i) \
;     __builtin_amdgcn_global_load_lds((const unsigned*)((const char*)(gbase) + (voff)[_i]), (LAS unsigned*)(lds + (bufoff) + ldsw + _i * 8192), 16, 0, 0); } while (0)
; #define PG8_LDA(dst, b, h) do { _Pragma("unroll") for (int m = 0; m < 4; ++m) _Pragma("unroll") for (int k = 0; k < 2; ++k) dst[m][k] = *(const LAS bf16x8*)(lds + PG8_SA(b, h) + aoff + m * 2048 + k * 1024); } while (0)
; #define PG8_LDB(dst, b, h) do { _Pragma("unroll") for (int n = 0; n < 2; ++n) _Pragma("unroll") for (int k = 0; k < 2; ++k) dst[n][k] = *(const LAS bf16x8*)(lds + PG8_SB(b, h) + boff + n * 2048 + k * 1024); } while (0)
; #define PG8_MMA(ai, bj, At, Bt) do { __builtin_amdgcn_s_setprio(1); _Pragma("unroll") for (int m = 0; m < 4; ++m) _Pragma("unroll") for (int n = 0; n < 2; ++n) _Pragma("unroll") for (int k = 0; k < 2; ++k) \
;     acc[ai][bj][m][n] = __builtin_amdgcn_mfma_f32_16x16x32_bf16(Bt[n][k], At[m][k], acc[ai][bj][m][n], 0, 0, 0); __builtin_amdgcn_s_setprio(0); } while (0)
; #define PG8_WAIT_L(n) asm volatile("s_waitcnt lgkmcnt(" #n ")" ::: "memory")
; #define PG8_BAR __builtin_amdgcn_s_barrier()
; #define PG8_SCHED __builtin_amdgcn_sched_barrier(0)
; template <class Epi, class Sched>
; DI void gemm_phase(LAS unsigned char* lds, const Gemm g, const Sched& S, const Epi& E) {
;     ...
;     for (int t = 0; t < nt; t += 2) {
;       const bool last = (t == nt - 2);
;       const char* a1 = cA + (size_t)(t + 1) * kstep;
;       const char* a2 = last ? nA : cA + (size_t)(t + 2) * kstep; const char* b2 = last ? nB : cB + (size_t)(t + 2) * kstep;
;       const char* a3 = a2 + kstep; const char* b3 = b2 + kstep;
;       PG8_LDB(B0, 0, 0); PG8_SCHED; PG8_LDA(At, 0, 0); PG8_STAGE(PG8_SA(1, 1), a1 + hstep, voffA);
;       PG8_WAIT_L(8); PG8_BAR; PG8_WAIT_L(0); PG8_MMA(0, 0, At, B0); PG8_BAR; PG8_SCHED;
;       PG8_LDB(B1, 0, 1); PG8_STAGE(PG8_SB(0, 0), b2, voffB);
;       PG8_BAR; PG8_WAIT_L(0); PG8_MMA(0, 1, At, B1); PG8_BAR;
;       PG8_LDA(At, 0, 1); PG8_STAGE(PG8_SA(0, 0), a2, voffA);
;       PG8_BAR; PG8_WAIT_L(0); PG8_MMA(1, 0, At, B0); PG8_BAR; PG8_SCHED;
;       PG8_STAGE(PG8_SB(0, 1), b2 + hstepB, voffB);
.LBB0_178:
	s_add_i32 s51, s24, 2
	s_add_u32 s26, s22, 0x80
	s_addc_u32 s25, s23, 0
	s_add_i32 s52, 16, 0x10000
	v_add_u32_e32 v156, s52, v141
	ds_read_b128 v[144:147], v156
	ds_read_b128 v[148:151], v156 offset:1024
	ds_read_b128 v[152:155], v156 offset:2048
	ds_read_b128 v[156:159], v156 offset:3072
	s_cmp_eq_u32 s43, s24
	s_cselect_b32 s24, s18, s26
	s_cselect_b32 s25, s19, s25
	s_cselect_b32 s27, s21, s50
	s_cselect_b32 s26, s20, s49
	ds_read_b128 v[160:163], v143
	ds_read_b128 v[164:167], v143 offset:1024
	ds_read_b128 v[168:171], v143 offset:2048
	ds_read_b128 v[172:175], v143 offset:3072
	ds_read_b128 v[186:189], v143 offset:4096
	ds_read_b128 v[190:193], v143 offset:5120
	ds_read_b128 v[198:201], v143 offset:6144
	ds_read_b128 v[202:205], v143 offset:7168
	s_add_i32 s53, 16, 0x14000
	v_add_u32_e32 v176, s53, v141
	s_add_i32 s52, s52, s35
	ds_read_b128 v[206:209], v176
	ds_read_b128 v[214:217], v176 offset:1024
	ds_read_b128 v[218:221], v176 offset:2048
	ds_read_b128 v[222:225], v176 offset:3072
	v_lshl_add_u64 v[176:177], s[22:23], 0, v[136:137]
	s_add_i32 m0, s36, 0xc000
	s_nop 0
	global_load_lds_dwordx4 v[176:177], off
	v_lshl_add_u64 v[176:177], s[22:23], 0, v[138:139]
	s_add_i32 m0, s36, 0xe000
	s_nop 0
	global_load_lds_dwordx4 v[176:177], off
	s_waitcnt lgkmcnt(0)
	s_barrier
	v_mfma_f32_16x16x32_bf16 v[122:125], v[144:147], v[160:163], v[122:125]
	v_mfma_f32_16x16x32_bf16 v[118:121], v[152:155], v[160:163], v[118:121]
	v_mfma_f32_16x16x32_bf16 v[110:113], v[144:147], v[168:171], v[110:113]
	v_mfma_f32_16x16x32_bf16 v[102:105], v[152:155], v[168:171], v[102:105]
	v_mfma_f32_16x16x32_bf16 v[94:97], v[144:147], v[186:189], v[94:97]
	v_mfma_f32_16x16x32_bf16 v[86:89], v[152:155], v[186:189], v[86:89]
	v_mfma_f32_16x16x32_bf16 v[78:81], v[144:147], v[198:201], v[78:81]
	v_mfma_f32_16x16x32_bf16 v[70:73], v[152:155], v[198:201], v[70:73]
	v_mfma_f32_16x16x32_bf16 v[122:125], v[148:151], v[164:167], v[122:125]
	v_mfma_f32_16x16x32_bf16 v[118:121], v[156:159], v[164:167], v[118:121]
	v_mfma_f32_16x16x32_bf16 v[110:113], v[148:151], v[172:175], v[110:113]
	v_mfma_f32_16x16x32_bf16 v[102:105], v[156:159], v[172:175], v[102:105]
	v_mfma_f32_16x16x32_bf16 v[94:97], v[148:151], v[190:193], v[94:97]
	v_mfma_f32_16x16x32_bf16 v[86:89], v[156:159], v[190:193], v[86:89]
	v_mfma_f32_16x16x32_bf16 v[78:81], v[148:151], v[202:205], v[78:81]
	v_mfma_f32_16x16x32_bf16 v[70:73], v[156:159], v[202:205], v[70:73]
	v_mfma_f32_16x16x32_bf16 v[126:129], v[206:209], v[160:163], v[126:129]
	v_mfma_f32_16x16x32_bf16 v[114:117], v[218:221], v[160:163], v[114:117]
	v_mfma_f32_16x16x32_bf16 v[106:109], v[206:209], v[168:171], v[106:109]
	v_mfma_f32_16x16x32_bf16 v[98:101], v[218:221], v[168:171], v[98:101]
	v_mfma_f32_16x16x32_bf16 v[90:93], v[206:209], v[186:189], v[90:93]
	v_mfma_f32_16x16x32_bf16 v[82:85], v[218:221], v[186:189], v[82:85]
	v_mfma_f32_16x16x32_bf16 v[74:77], v[206:209], v[198:201], v[74:77]
	v_mfma_f32_16x16x32_bf16 v[66:69], v[218:221], v[198:201], v[66:69]
	v_mfma_f32_16x16x32_bf16 v[126:129], v[214:217], v[164:167], v[126:129]
	v_mfma_f32_16x16x32_bf16 v[114:117], v[222:225], v[164:167], v[114:117]
	v_mfma_f32_16x16x32_bf16 v[106:109], v[214:217], v[172:175], v[106:109]
	v_mfma_f32_16x16x32_bf16 v[98:101], v[222:225], v[172:175], v[98:101]
	v_mfma_f32_16x16x32_bf16 v[90:93], v[214:217], v[190:193], v[90:93]
	v_mfma_f32_16x16x32_bf16 v[82:85], v[222:225], v[190:193], v[82:85]
	v_mfma_f32_16x16x32_bf16 v[74:77], v[214:217], v[202:205], v[74:77]
	v_mfma_f32_16x16x32_bf16 v[66:69], v[222:225], v[202:205], v[66:69]
	s_mov_b32 m0, s36
	v_lshl_add_u64 v[182:183], s[24:25], 0, v[134:135]
	s_barrier
	ds_read_b128 v[160:163], v143 offset:16384
	ds_read_b128 v[164:167], v143 offset:17408
	ds_read_b128 v[168:171], v143 offset:18432
	ds_read_b128 v[172:175], v143 offset:19456
	ds_read_b128 v[186:189], v143 offset:20480
	ds_read_b128 v[190:193], v143 offset:21504
	ds_read_b128 v[198:201], v143 offset:22528
	ds_read_b128 v[202:205], v143 offset:23552
	global_load_lds_dwordx4 v[182:183], off
	v_lshl_add_u64 v[184:185], s[24:25], 0, v[132:133]
	s_mov_b32 m0, s37
	s_nop 0
	global_load_lds_dwordx4 v[184:185], off
	v_lshl_add_u64 v[230:231], s[26:27], 0, v[0:1]
	s_mov_b32 m0, s52
	v_lshl_add_u64 v[180:181], s[26:27], 0, v[130:131]
	global_load_lds_dwordx4 v[230:231], off
	s_add_i32 m0, s52, 0x2000
	s_nop 0
	global_load_lds_dwordx4 v[180:181], off
	s_add_u32 s26, s26, s0
	s_addc_u32 s27, s27, s1
	s_add_i32 s52, s53, s35
	v_lshl_add_u64 v[226:227], s[26:27], 0, v[0:1]
	s_mov_b32 m0, s52
	v_lshl_add_u64 v[228:229], s[26:27], 0, v[130:131]
	global_load_lds_dwordx4 v[226:227], off
	s_add_i32 m0, s52, 0x2000
	s_nop 0
	global_load_lds_dwordx4 v[228:229], off
	s_waitcnt vmcnt(6)
	s_waitcnt lgkmcnt(0)
	s_barrier
; #define PG8_STAGE(bufoff, gbase, voff) do { _Pragma("unroll") for (int _i = 0; _i < 2; ++_i) \
;     __builtin_amdgcn_global_load_lds((const unsigned*)((const char*)(gbase) + (voff)[_i]), (LAS unsigned*)(lds + (bufoff) + ldsw + _i * 8192), 16, 0, 0); } while (0)
; #define PG8_LDA(dst, b, h) do { _Pragma("unroll") for (int m = 0; m < 4; ++m) _Pragma("unroll") for (int k = 0; k < 2; ++k) dst[m][k] = *(const LAS bf16x8*)(lds + PG8_SA(b, h) + aoff + m * 2048 + k * 1024); } while (0)
; #define PG8_LDB(dst, b, h) do { _Pragma("unroll") for (int n = 0; n < 2; ++n) _Pragma("unroll") for (int k = 0; k < 2; ++k) dst[n][k] = *(const LAS bf16x8*)(lds + PG8_SB(b, h) + boff + n * 2048 + k * 1024); } while (0)
; #define PG8_MMA(ai, bj, At, Bt) do { __builtin_amdgcn_s_setprio(1); _Pragma("unroll") for (int m = 0; m < 4; ++m) _Pragma("unroll") for (int n = 0; n < 2; ++n) _Pragma("unroll") for (int k = 0; k < 2; ++k) \
;     acc[ai][bj][m][n] = __builtin_amdgcn_mfma_f32_16x16x32_bf16(Bt[n][k], At[m][k], acc[ai][bj][m][n], 0, 0, 0); __builtin_amdgcn_s_setprio(0); } while (0)
; #define PG8_WAIT_V(n) asm volatile("s_waitcnt vmcnt(" #n ")" ::: "memory")
; #define PG8_WAIT_L(n) asm volatile("s_waitcnt lgkmcnt(" #n ")" ::: "memory")
; #define PG8_BAR __builtin_amdgcn_s_barrier()
; #define PG8_SCHED __builtin_amdgcn_sched_barrier(0)
; template <class Epi, class Sched>
; DI void gemm_phase(LAS unsigned char* lds, const Gemm g, const Sched& S, const Epi& E) {
;     ...
;       PG8_BAR; PG8_WAIT_L(0); PG8_MMA(1, 0, At, B0); PG8_BAR; PG8_SCHED;
;       PG8_STAGE(PG8_SB(0, 1), b2 + hstepB, voffB);
;       PG8_WAIT_V(6); PG8_BAR; PG8_MMA(1, 1, At, B1); PG8_BAR;
;       PG8_LDB(B0, 1, 0); PG8_SCHED; PG8_LDA(At, 1, 0); PG8_STAGE(PG8_SA(0, 1), a2 + hstep, voffA);
;       PG8_WAIT_L(8); PG8_BAR; PG8_WAIT_L(0); PG8_MMA(0, 0, At, B0); PG8_BAR; PG8_SCHED;
;       PG8_LDB(B1, 1, 1); PG8_STAGE(PG8_SB(1, 0), b3, voffB);
;       PG8_BAR; PG8_WAIT_L(0); PG8_MMA(0, 1, At, B1); PG8_BAR;
	v_mfma_f32_16x16x32_bf16 v[62:65], v[144:147], v[160:163], v[62:65]
	v_mfma_f32_16x16x32_bf16 v[54:57], v[152:155], v[160:163], v[54:57]
	v_mfma_f32_16x16x32_bf16 v[46:49], v[144:147], v[168:171], v[46:49]
	v_mfma_f32_16x16x32_bf16 v[38:41], v[152:155], v[168:171], v[38:41]
	v_mfma_f32_16x16x32_bf16 v[30:33], v[144:147], v[186:189], v[30:33]
	v_mfma_f32_16x16x32_bf16 v[22:25], v[152:155], v[186:189], v[22:25]
	v_mfma_f32_16x16x32_bf16 v[14:17], v[144:147], v[198:201], v[14:17]
	v_mfma_f32_16x16x32_bf16 v[6:9], v[152:155], v[198:201], v[6:9]
	v_mfma_f32_16x16x32_bf16 v[62:65], v[148:151], v[164:167], v[62:65]
	v_mfma_f32_16x16x32_bf16 v[54:57], v[156:159], v[164:167], v[54:57]
	v_mfma_f32_16x16x32_bf16 v[46:49], v[148:151], v[172:175], v[46:49]
	v_mfma_f32_16x16x32_bf16 v[38:41], v[156:159], v[172:175], v[38:41]
	v_mfma_f32_16x16x32_bf16 v[30:33], v[148:151], v[190:193], v[30:33]
	v_mfma_f32_16x16x32_bf16 v[22:25], v[156:159], v[190:193], v[22:25]
	v_mfma_f32_16x16x32_bf16 v[14:17], v[148:151], v[202:205], v[14:17]
	v_mfma_f32_16x16x32_bf16 v[6:9], v[156:159], v[202:205], v[6:9]
	v_mfma_f32_16x16x32_bf16 v[58:61], v[206:209], v[160:163], v[58:61]
	v_mfma_f32_16x16x32_bf16 v[50:53], v[218:221], v[160:163], v[50:53]
	v_mfma_f32_16x16x32_bf16 v[42:45], v[206:209], v[168:171], v[42:45]
	v_mfma_f32_16x16x32_bf16 v[34:37], v[218:221], v[168:171], v[34:37]
	v_mfma_f32_16x16x32_bf16 v[26:29], v[206:209], v[186:189], v[26:29]
	v_mfma_f32_16x16x32_bf16 v[18:21], v[218:221], v[186:189], v[18:21]
	v_mfma_f32_16x16x32_bf16 v[10:13], v[206:209], v[198:201], v[10:13]
	v_mfma_f32_16x16x32_bf16 v[2:5], v[218:221], v[198:201], v[2:5]
	v_mfma_f32_16x16x32_bf16 v[58:61], v[214:217], v[164:167], v[58:61]
	v_mfma_f32_16x16x32_bf16 v[50:53], v[222:225], v[164:167], v[50:53]
	v_mfma_f32_16x16x32_bf16 v[42:45], v[214:217], v[172:175], v[42:45]
	v_mfma_f32_16x16x32_bf16 v[34:37], v[222:225], v[172:175], v[34:37]
	v_mfma_f32_16x16x32_bf16 v[26:29], v[214:217], v[190:193], v[26:29]
	v_mfma_f32_16x16x32_bf16 v[18:21], v[222:225], v[190:193], v[18:21]
	v_mfma_f32_16x16x32_bf16 v[10:13], v[214:217], v[202:205], v[10:13]
	v_mfma_f32_16x16x32_bf16 v[2:5], v[222:225], v[202:205], v[2:5]
	s_add_i32 s26, 16, 0x18000
	v_add_u32_e32 v156, s26, v141
	s_barrier
	ds_read_b128 v[144:147], v156
	ds_read_b128 v[148:151], v156 offset:1024
	ds_read_b128 v[152:155], v156 offset:2048
	ds_read_b128 v[156:159], v156 offset:3072
	s_add_u32 s24, s24, s0
	s_addc_u32 s25, s25, s1
	ds_read_b128 v[160:163], v143 offset:32768
	ds_read_b128 v[164:167], v143 offset:33792
	ds_read_b128 v[168:171], v143 offset:34816
	ds_read_b128 v[172:175], v143 offset:35840
	ds_read_b128 v[186:189], v143 offset:36864
	ds_read_b128 v[190:193], v143 offset:37888
	ds_read_b128 v[198:201], v143 offset:38912
	ds_read_b128 v[202:205], v143 offset:39936
	v_lshl_add_u64 v[232:233], s[24:25], 0, v[134:135]
	v_lshl_add_u64 v[234:235], s[24:25], 0, v[132:133]
	s_add_i32 s24, 16, 0x1c000
	s_add_i32 s25, s26, s35
	v_add_u32_e32 v194, s24, v141
	ds_read_b128 v[206:209], v194
	ds_read_b128 v[214:217], v194 offset:1024
	ds_read_b128 v[218:221], v194 offset:2048
	ds_read_b128 v[222:225], v194 offset:3072
	s_mov_b32 m0, s38
	s_nop 0
	global_load_lds_dwordx4 v[232:233], off
	s_mov_b32 m0, s39
	s_nop 0
	global_load_lds_dwordx4 v[234:235], off
	s_waitcnt lgkmcnt(0)
	s_barrier
	v_mfma_f32_16x16x32_bf16 v[122:125], v[144:147], v[160:163], v[122:125]
	v_mfma_f32_16x16x32_bf16 v[118:121], v[152:155], v[160:163], v[118:121]
	v_mfma_f32_16x16x32_bf16 v[110:113], v[144:147], v[168:171], v[110:113]
	v_mfma_f32_16x16x32_bf16 v[102:105], v[152:155], v[168:171], v[102:105]
	v_mfma_f32_16x16x32_bf16 v[94:97], v[144:147], v[186:189], v[94:97]
	v_mfma_f32_16x16x32_bf16 v[86:89], v[152:155], v[186:189], v[86:89]
	v_mfma_f32_16x16x32_bf16 v[78:81], v[144:147], v[198:201], v[78:81]
	v_mfma_f32_16x16x32_bf16 v[70:73], v[152:155], v[198:201], v[70:73]
	v_mfma_f32_16x16x32_bf16 v[122:125], v[148:151], v[164:167], v[122:125]
	v_mfma_f32_16x16x32_bf16 v[118:121], v[156:159], v[164:167], v[118:121]
	v_mfma_f32_16x16x32_bf16 v[110:113], v[148:151], v[172:175], v[110:113]
	v_mfma_f32_16x16x32_bf16 v[102:105], v[156:159], v[172:175], v[102:105]
	v_mfma_f32_16x16x32_bf16 v[94:97], v[148:151], v[190:193], v[94:97]
	v_mfma_f32_16x16x32_bf16 v[86:89], v[156:159], v[190:193], v[86:89]
	v_mfma_f32_16x16x32_bf16 v[78:81], v[148:151], v[202:205], v[78:81]
	v_mfma_f32_16x16x32_bf16 v[70:73], v[156:159], v[202:205], v[70:73]
	v_mfma_f32_16x16x32_bf16 v[126:129], v[206:209], v[160:163], v[126:129]
	v_mfma_f32_16x16x32_bf16 v[114:117], v[218:221], v[160:163], v[114:117]
	v_mfma_f32_16x16x32_bf16 v[106:109], v[206:209], v[168:171], v[106:109]
	v_mfma_f32_16x16x32_bf16 v[98:101], v[218:221], v[168:171], v[98:101]
	v_mfma_f32_16x16x32_bf16 v[90:93], v[206:209], v[186:189], v[90:93]
	v_mfma_f32_16x16x32_bf16 v[82:85], v[218:221], v[186:189], v[82:85]
	v_mfma_f32_16x16x32_bf16 v[74:77], v[206:209], v[198:201], v[74:77]
	v_mfma_f32_16x16x32_bf16 v[66:69], v[218:221], v[198:201], v[66:69]
	v_mfma_f32_16x16x32_bf16 v[126:129], v[214:217], v[164:167], v[126:129]
	v_mfma_f32_16x16x32_bf16 v[114:117], v[222:225], v[164:167], v[114:117]
	v_mfma_f32_16x16x32_bf16 v[106:109], v[214:217], v[172:175], v[106:109]
	v_mfma_f32_16x16x32_bf16 v[98:101], v[222:225], v[172:175], v[98:101]
	v_mfma_f32_16x16x32_bf16 v[90:93], v[214:217], v[190:193], v[90:93]
	v_mfma_f32_16x16x32_bf16 v[82:85], v[222:225], v[190:193], v[82:85]
	v_mfma_f32_16x16x32_bf16 v[74:77], v[214:217], v[202:205], v[74:77]
	v_mfma_f32_16x16x32_bf16 v[66:69], v[222:225], v[202:205], v[66:69]
	s_mov_b32 m0, s41
	v_lshl_add_u64 v[176:177], v[182:183], 0, s[70:71]
	s_barrier
; #define PG8_STAGE(bufoff, gbase, voff) do { _Pragma("unroll") for (int _i = 0; _i < 2; ++_i) \
;     __builtin_amdgcn_global_load_lds((const unsigned*)((const char*)(gbase) + (voff)[_i]), (LAS unsigned*)(lds + (bufoff) + ldsw + _i * 8192), 16, 0, 0); } while (0)
; #define PG8_LDA(dst, b, h) do { _Pragma("unroll") for (int m = 0; m < 4; ++m) _Pragma("unroll") for (int k = 0; k < 2; ++k) dst[m][k] = *(const LAS bf16x8*)(lds + PG8_SA(b, h) + aoff + m * 2048 + k * 1024); } while (0)
; #define PG8_MMA(ai, bj, At, Bt) do { __builtin_amdgcn_s_setprio(1); _Pragma("unroll") for (int m = 0; m < 4; ++m) _Pragma("unroll") for (int n = 0; n < 2; ++n) _Pragma("unroll") for (int k = 0; k < 2; ++k) \
;     acc[ai][bj][m][n] = __builtin_amdgcn_mfma_f32_16x16x32_bf16(Bt[n][k], At[m][k], acc[ai][bj][m][n], 0, 0, 0); __builtin_amdgcn_s_setprio(0); } while (0)
; #define PG8_WAIT_V(n) asm volatile("s_waitcnt vmcnt(" #n ")" ::: "memory")
; #define PG8_WAIT_L(n) asm volatile("s_waitcnt lgkmcnt(" #n ")" ::: "memory")
; #define PG8_BAR __builtin_amdgcn_s_barrier()
; #define PG8_SCHED __builtin_amdgcn_sched_barrier(0)
; template <class Epi, class Sched>
; DI void gemm_phase(LAS unsigned char* lds, const Gemm g, const Sched& S, const Epi& E) {
;     ...
;       PG8_LDA(At, 1, 1); PG8_STAGE(PG8_SA(1, 0), a3, voffA);
;       PG8_BAR; PG8_WAIT_L(0); PG8_MMA(1, 0, At, B0); PG8_BAR; PG8_SCHED;
;       PG8_STAGE(PG8_SB(1, 1), b3 + hstepB, voffB);
;       PG8_WAIT_V(6); PG8_BAR; PG8_MMA(1, 1, At, B1); PG8_BAR;
	ds_read_b128 v[160:163], v143 offset:49152
	ds_read_b128 v[164:167], v143 offset:50176
	ds_read_b128 v[168:171], v143 offset:51200
	ds_read_b128 v[172:175], v143 offset:52224
	ds_read_b128 v[186:189], v143 offset:53248
	ds_read_b128 v[190:193], v143 offset:54272
	ds_read_b128 v[198:201], v143 offset:55296
	ds_read_b128 v[202:205], v143 offset:56320
	global_load_lds_dwordx4 v[176:177], off
	v_lshl_add_u64 v[176:177], v[184:185], 0, s[70:71]
	s_mov_b32 m0, s42
	s_nop 0
	global_load_lds_dwordx4 v[176:177], off
	s_mov_b32 m0, s25
	v_lshl_add_u64 v[230:231], v[230:231], 0, s[70:71]
	global_load_lds_dwordx4 v[230:231], off
	v_lshl_add_u64 v[176:177], v[180:181], 0, s[70:71]
	s_add_i32 m0, s25, 0x2000
	s_nop 0
	global_load_lds_dwordx4 v[176:177], off
	s_add_i32 s24, s24, s35
	v_lshl_add_u64 v[232:233], v[226:227], 0, s[70:71]
	s_mov_b32 m0, s24
	s_nop 0
	global_load_lds_dwordx4 v[232:233], off
	v_lshl_add_u64 v[232:233], v[228:229], 0, s[70:71]
	s_add_i32 m0, s24, 0x2000
	s_nop 0
	global_load_lds_dwordx4 v[232:233], off
	s_waitcnt vmcnt(6)
	s_waitcnt lgkmcnt(0)
	s_barrier
	v_mfma_f32_16x16x32_bf16 v[62:65], v[144:147], v[160:163], v[62:65]
	v_mfma_f32_16x16x32_bf16 v[54:57], v[152:155], v[160:163], v[54:57]
	v_mfma_f32_16x16x32_bf16 v[46:49], v[144:147], v[168:171], v[46:49]
	v_mfma_f32_16x16x32_bf16 v[38:41], v[152:155], v[168:171], v[38:41]
	v_mfma_f32_16x16x32_bf16 v[30:33], v[144:147], v[186:189], v[30:33]
	v_mfma_f32_16x16x32_bf16 v[22:25], v[152:155], v[186:189], v[22:25]
	v_mfma_f32_16x16x32_bf16 v[14:17], v[144:147], v[198:201], v[14:17]
	v_mfma_f32_16x16x32_bf16 v[6:9], v[152:155], v[198:201], v[6:9]
	v_mfma_f32_16x16x32_bf16 v[62:65], v[148:151], v[164:167], v[62:65]
	v_mfma_f32_16x16x32_bf16 v[54:57], v[156:159], v[164:167], v[54:57]
	v_mfma_f32_16x16x32_bf16 v[46:49], v[148:151], v[172:175], v[46:49]
	v_mfma_f32_16x16x32_bf16 v[38:41], v[156:159], v[172:175], v[38:41]
	v_mfma_f32_16x16x32_bf16 v[30:33], v[148:151], v[190:193], v[30:33]
	v_mfma_f32_16x16x32_bf16 v[22:25], v[156:159], v[190:193], v[22:25]
	v_mfma_f32_16x16x32_bf16 v[14:17], v[148:151], v[202:205], v[14:17]
	v_mfma_f32_16x16x32_bf16 v[6:9], v[156:159], v[202:205], v[6:9]
	v_mfma_f32_16x16x32_bf16 v[58:61], v[206:209], v[160:163], v[58:61]
	v_mfma_f32_16x16x32_bf16 v[50:53], v[218:221], v[160:163], v[50:53]
	v_mfma_f32_16x16x32_bf16 v[42:45], v[206:209], v[168:171], v[42:45]
	v_mfma_f32_16x16x32_bf16 v[34:37], v[218:221], v[168:171], v[34:37]
	v_mfma_f32_16x16x32_bf16 v[26:29], v[206:209], v[186:189], v[26:29]
	v_mfma_f32_16x16x32_bf16 v[18:21], v[218:221], v[186:189], v[18:21]
	v_mfma_f32_16x16x32_bf16 v[10:13], v[206:209], v[198:201], v[10:13]
	v_mfma_f32_16x16x32_bf16 v[2:5], v[218:221], v[198:201], v[2:5]
	v_mfma_f32_16x16x32_bf16 v[58:61], v[214:217], v[164:167], v[58:61]
	v_mfma_f32_16x16x32_bf16 v[50:53], v[222:225], v[164:167], v[50:53]
	v_mfma_f32_16x16x32_bf16 v[42:45], v[214:217], v[172:175], v[42:45]
	v_mfma_f32_16x16x32_bf16 v[34:37], v[222:225], v[172:175], v[34:37]
	v_mfma_f32_16x16x32_bf16 v[26:29], v[214:217], v[190:193], v[26:29]
	v_mfma_f32_16x16x32_bf16 v[18:21], v[222:225], v[190:193], v[18:21]
	v_mfma_f32_16x16x32_bf16 v[10:13], v[214:217], v[202:205], v[10:13]
	v_mfma_f32_16x16x32_bf16 v[2:5], v[222:225], v[202:205], v[2:5]
	s_add_u32 s22, s22, 0x100
	s_addc_u32 s23, s23, 0
	s_add_u32 s49, s49, 0x100
	s_addc_u32 s50, s50, 0
	s_cmp_ge_i32 s51, s40
	s_mov_b32 s24, s51
	s_barrier
	s_cbranch_scc0 .LBB0_178
	s_branch .LBB0_161
